# GEMM K-loops with inverted priority flips (raised during the load segment, lowered during the MFMA block)
# baseline (speedup 1.0000x reference)
; #define PG8_STAGE(bufoff, gbase, voff) do { _Pragma("unroll") for (int _i = 0; _i < 2; ++_i) \
;         __builtin_amdgcn_global_load_lds((const unsigned*)((const char*)(gbase) + (voff)[_i]), (LAS unsigned*)(lds + (bufoff) + ldsw + _i * 8192), 16, 0, 0); } while (0)
; #define PG8_LDA(dst, b, h) do { _Pragma("unroll") for (int m = 0; m < 4; ++m) _Pragma("unroll") for (int k = 0; k < 2; ++k) dst[m][k] = *(const LAS bf16x8*)(lds + PG8_SA(b, h) + aoff + m * 2048 + k * 1024); } while (0)
; #define PG8_LDB(dst, b, h) do { _Pragma("unroll") for (int n = 0; n < 2; ++n) _Pragma("unroll") for (int k = 0; k < 2; ++k) dst[n][k] = *(const LAS bf16x8*)(lds + PG8_SB(b, h) + boff + n * 2048 + k * 1024); } while (0)
; #define PG8_MMA(ai, bj, At, Bt) do { __builtin_amdgcn_s_setprio(1); _Pragma("unroll") for (int m = 0; m < 4; ++m) _Pragma("unroll") for (int n = 0; n < 2; ++n) _Pragma("unroll") for (int k = 0; k < 2; ++k) \
;         acc[ai][bj][m][n] = __builtin_amdgcn_mfma_f32_16x16x32_bf16(Bt[n][k], At[m][k], acc[ai][bj][m][n], 0, 0, 0); __builtin_amdgcn_s_setprio(0); } while (0)
; #define PG8_WAIT_L(n) asm volatile("s_waitcnt lgkmcnt(" #n ")" ::: "memory")
; #define PG8_BAR __builtin_amdgcn_s_barrier()
; #define PG8_SCHED __builtin_amdgcn_sched_barrier(0)
; template <class Epi>
; __device__ __forceinline__ void gemm_phase(LAS unsigned char* lds, const Gemm g, const StaticOrder& S, const Epi& E) {
;     ...
;             PG8_LDB(B0, 0, 0); PG8_SCHED; PG8_LDA(At, 0, 0); PG8_STAGE(PG8_SA(1, 1), a1 + hstep, voffA);
;             PG8_WAIT_L(8); PG8_BAR; PG8_WAIT_L(0); PG8_MMA(0, 0, At, B0); PG8_BAR; PG8_SCHED;
;             PG8_LDB(B1, 0, 1); PG8_STAGE(PG8_SB(0, 0), b2, voffB);
;             PG8_BAR; PG8_WAIT_L(0); PG8_MMA(0, 1, At, B1); PG8_BAR;
;             PG8_LDA(At, 0, 1); PG8_STAGE(PG8_SA(0, 0), a2, voffA);
;             PG8_BAR; PG8_WAIT_L(0); PG8_MMA(1, 0, At, B0); PG8_BAR; PG8_SCHED;
.LBB0_80:
	ds_read_b128 v[154:157], v173
	ds_read_b128 v[176:179], v173 offset:1024
	ds_read_b128 v[180:183], v173 offset:2048
	ds_read_b128 v[184:187], v173 offset:3072
	s_add_u32 s26, s12, 0xfff80080
	s_addc_u32 s27, s13, -1
	s_cmp_eq_u32 s67, 28
	s_cselect_b32 s29, s7, s27
	s_cselect_b32 s28, s63, s26
	s_cselect_b32 s27, s25, s66
	s_cselect_b32 s26, s64, s65
	v_lshl_add_u64 v[220:221], s[12:13], 0, v[146:147]
	s_add_i32 m0, s42, 0xc000
	ds_read_b128 v[188:191], v174
	ds_read_b128 v[192:195], v174 offset:1024
	ds_read_b128 v[196:199], v174 offset:2048
	ds_read_b128 v[200:203], v174 offset:3072
	ds_read_b128 v[204:207], v174 offset:4096
	ds_read_b128 v[208:211], v174 offset:5120
	ds_read_b128 v[212:215], v174 offset:6144
	ds_read_b128 v[216:219], v174 offset:7168
	global_load_lds_dwordx4 v[220:221], off
	v_lshl_add_u64 v[220:221], s[12:13], 0, v[148:149]
	s_add_i32 m0, s42, 0xe000
	s_nop 0
	global_load_lds_dwordx4 v[220:221], off
	s_waitcnt lgkmcnt(8)
	s_barrier
	s_waitcnt lgkmcnt(0)
	s_setprio 0
	s_waitcnt lgkmcnt(0)
	v_mfma_f32_16x16x32_bf16 v[124:127], v[154:157], v[188:191], v[124:127]
	v_mfma_f32_16x16x32_bf16 v[120:123], v[180:183], v[188:191], v[120:123]
	v_mfma_f32_16x16x32_bf16 v[116:119], v[154:157], v[196:199], v[116:119]
	v_mfma_f32_16x16x32_bf16 v[112:115], v[180:183], v[196:199], v[112:115]
	v_mfma_f32_16x16x32_bf16 v[100:103], v[154:157], v[204:207], v[100:103]
	v_mfma_f32_16x16x32_bf16 v[96:99], v[180:183], v[204:207], v[96:99]
	v_mfma_f32_16x16x32_bf16 v[76:79], v[154:157], v[212:215], v[76:79]
	v_mfma_f32_16x16x32_bf16 v[72:75], v[180:183], v[212:215], v[72:75]
	v_mfma_f32_16x16x32_bf16 v[124:127], v[176:179], v[192:195], v[124:127]
	v_mfma_f32_16x16x32_bf16 v[120:123], v[184:187], v[192:195], v[120:123]
	v_mfma_f32_16x16x32_bf16 v[116:119], v[176:179], v[200:203], v[116:119]
	v_mfma_f32_16x16x32_bf16 v[112:115], v[184:187], v[200:203], v[112:115]
	v_mfma_f32_16x16x32_bf16 v[100:103], v[176:179], v[208:211], v[100:103]
	v_mfma_f32_16x16x32_bf16 v[96:99], v[184:187], v[208:211], v[96:99]
	v_mfma_f32_16x16x32_bf16 v[76:79], v[176:179], v[216:219], v[76:79]
	v_mfma_f32_16x16x32_bf16 v[72:75], v[184:187], v[216:219], v[72:75]
	s_setprio 1
	s_barrier
	s_add_i32 s68, s55, s35
	v_lshl_add_u64 v[236:237], s[26:27], 0, v[140:141]
	s_mov_b32 m0, s68
	ds_read_b128 v[220:223], v175
	ds_read_b128 v[224:227], v175 offset:1024
	ds_read_b128 v[228:231], v175 offset:2048
	ds_read_b128 v[232:235], v175 offset:3072
	global_load_lds_dwordx4 v[236:237], off
	v_lshl_add_u64 v[238:239], s[26:27], 0, v[136:137]
	s_add_i32 m0, s68, 0x2000
	s_nop 0
	global_load_lds_dwordx4 v[238:239], off
	s_barrier
	s_waitcnt lgkmcnt(0)
	s_setprio 0
	s_waitcnt lgkmcnt(0)
	v_mfma_f32_16x16x32_bf16 v[108:111], v[220:223], v[188:191], v[108:111]
	v_mfma_f32_16x16x32_bf16 v[104:107], v[228:231], v[188:191], v[104:107]
	v_mfma_f32_16x16x32_bf16 v[92:95], v[220:223], v[196:199], v[92:95]
	v_mfma_f32_16x16x32_bf16 v[88:91], v[228:231], v[196:199], v[88:91]
	v_mfma_f32_16x16x32_bf16 v[84:87], v[220:223], v[204:207], v[84:87]
	v_mfma_f32_16x16x32_bf16 v[80:83], v[228:231], v[204:207], v[80:83]
	v_mfma_f32_16x16x32_bf16 v[68:71], v[220:223], v[212:215], v[68:71]
	v_mfma_f32_16x16x32_bf16 v[64:67], v[228:231], v[212:215], v[64:67]
	v_mfma_f32_16x16x32_bf16 v[108:111], v[224:227], v[192:195], v[108:111]
	v_mfma_f32_16x16x32_bf16 v[104:107], v[232:235], v[192:195], v[104:107]
	v_mfma_f32_16x16x32_bf16 v[92:95], v[224:227], v[200:203], v[92:95]
	v_mfma_f32_16x16x32_bf16 v[88:91], v[232:235], v[200:203], v[88:91]
	v_mfma_f32_16x16x32_bf16 v[84:87], v[224:227], v[208:211], v[84:87]
	v_mfma_f32_16x16x32_bf16 v[80:83], v[232:235], v[208:211], v[80:83]
	v_mfma_f32_16x16x32_bf16 v[68:71], v[224:227], v[216:219], v[68:71]
	v_mfma_f32_16x16x32_bf16 v[64:67], v[232:235], v[216:219], v[64:67]
	s_setprio 1
	s_mov_b32 m0, s42
	v_lshl_add_u64 v[240:241], s[28:29], 0, v[142:143]
	s_barrier
	ds_read_b128 v[188:191], v174 offset:16384
	ds_read_b128 v[192:195], v174 offset:17408
	ds_read_b128 v[196:199], v174 offset:18432
	ds_read_b128 v[200:203], v174 offset:19456
	ds_read_b128 v[204:207], v174 offset:20480
	ds_read_b128 v[208:211], v174 offset:21504
	ds_read_b128 v[212:215], v174 offset:22528
	ds_read_b128 v[216:219], v174 offset:23552
	global_load_lds_dwordx4 v[240:241], off
	v_lshl_add_u64 v[242:243], s[28:29], 0, v[138:139]
	s_mov_b32 m0, s43
	s_nop 0
	global_load_lds_dwordx4 v[242:243], off
	s_barrier
	s_waitcnt lgkmcnt(0)
	s_setprio 0
	s_waitcnt lgkmcnt(0)
	v_mfma_f32_16x16x32_bf16 v[60:63], v[154:157], v[188:191], v[60:63]
	v_mfma_f32_16x16x32_bf16 v[56:59], v[180:183], v[188:191], v[56:59]
	v_mfma_f32_16x16x32_bf16 v[52:55], v[154:157], v[196:199], v[52:55]
	v_mfma_f32_16x16x32_bf16 v[48:51], v[180:183], v[196:199], v[48:51]
	v_mfma_f32_16x16x32_bf16 v[36:39], v[154:157], v[204:207], v[36:39]
	v_mfma_f32_16x16x32_bf16 v[32:35], v[180:183], v[204:207], v[32:35]
	v_mfma_f32_16x16x32_bf16 v[12:15], v[154:157], v[212:215], v[12:15]
	v_mfma_f32_16x16x32_bf16 v[8:11], v[180:183], v[212:215], v[8:11]
	v_mfma_f32_16x16x32_bf16 v[60:63], v[176:179], v[192:195], v[60:63]
	v_mfma_f32_16x16x32_bf16 v[56:59], v[184:187], v[192:195], v[56:59]
	v_mfma_f32_16x16x32_bf16 v[52:55], v[176:179], v[200:203], v[52:55]
	v_mfma_f32_16x16x32_bf16 v[48:51], v[184:187], v[200:203], v[48:51]
	v_mfma_f32_16x16x32_bf16 v[36:39], v[176:179], v[208:211], v[36:39]
	v_mfma_f32_16x16x32_bf16 v[32:35], v[184:187], v[208:211], v[32:35]
	v_mfma_f32_16x16x32_bf16 v[12:15], v[176:179], v[216:219], v[12:15]
	v_mfma_f32_16x16x32_bf16 v[8:11], v[184:187], v[216:219], v[8:11]
	s_setprio 1
	s_barrier
; #define PG8_STAGE(bufoff, gbase, voff) do { _Pragma("unroll") for (int _i = 0; _i < 2; ++_i) \
;         __builtin_amdgcn_global_load_lds((const unsigned*)((const char*)(gbase) + (voff)[_i]), (LAS unsigned*)(lds + (bufoff) + ldsw + _i * 8192), 16, 0, 0); } while (0)
; #define PG8_LDA(dst, b, h) do { _Pragma("unroll") for (int m = 0; m < 4; ++m) _Pragma("unroll") for (int k = 0; k < 2; ++k) dst[m][k] = *(const LAS bf16x8*)(lds + PG8_SA(b, h) + aoff + m * 2048 + k * 1024); } while (0)
; #define PG8_LDB(dst, b, h) do { _Pragma("unroll") for (int n = 0; n < 2; ++n) _Pragma("unroll") for (int k = 0; k < 2; ++k) dst[n][k] = *(const LAS bf16x8*)(lds + PG8_SB(b, h) + boff + n * 2048 + k * 1024); } while (0)
; #define PG8_MMA(ai, bj, At, Bt) do { __builtin_amdgcn_s_setprio(1); _Pragma("unroll") for (int m = 0; m < 4; ++m) _Pragma("unroll") for (int n = 0; n < 2; ++n) _Pragma("unroll") for (int k = 0; k < 2; ++k) \
;         acc[ai][bj][m][n] = __builtin_amdgcn_mfma_f32_16x16x32_bf16(Bt[n][k], At[m][k], acc[ai][bj][m][n], 0, 0, 0); __builtin_amdgcn_s_setprio(0); } while (0)
; #define PG8_WAIT_V(n) asm volatile("s_waitcnt vmcnt(" #n ")" ::: "memory")
; #define PG8_WAIT_L(n) asm volatile("s_waitcnt lgkmcnt(" #n ")" ::: "memory")
; #define PG8_BAR __builtin_amdgcn_s_barrier()
; #define PG8_SCHED __builtin_amdgcn_sched_barrier(0)
; template <class Epi>
; __device__ __forceinline__ void gemm_phase(LAS unsigned char* lds, const Gemm g, const StaticOrder& S, const Epi& E) {
;     ...
;             PG8_STAGE(PG8_SB(0, 1), b2 + hstep, voffB);
;             PG8_WAIT_V(6); PG8_BAR; PG8_MMA(1, 1, At, B1); PG8_BAR;
;             PG8_LDB(B0, 1, 0); PG8_SCHED; PG8_LDA(At, 1, 0); PG8_STAGE(PG8_SA(0, 1), a2 + hstep, voffA);
;             PG8_WAIT_L(8); PG8_BAR; PG8_WAIT_L(0); PG8_MMA(0, 0, At, B0); PG8_BAR; PG8_SCHED;
;             PG8_LDB(B1, 1, 1); PG8_STAGE(PG8_SB(1, 0), b3, voffB);
;             PG8_BAR; PG8_WAIT_L(0); PG8_MMA(0, 1, At, B1); PG8_BAR;
;             PG8_LDA(At, 1, 1); PG8_STAGE(PG8_SA(1, 0), a3, voffA);
	s_add_u32 s68, s26, 0x80000
	s_addc_u32 s69, s27, 0
	s_add_i32 s70, s56, s35
	v_lshl_add_u64 v[154:155], s[68:69], 0, v[140:141]
	s_mov_b32 m0, s70
	s_nop 0
	global_load_lds_dwordx4 v[154:155], off
	v_lshl_add_u64 v[154:155], s[68:69], 0, v[136:137]
	s_add_i32 m0, s70, 0x2000
	s_nop 0
	global_load_lds_dwordx4 v[154:155], off
	s_waitcnt vmcnt(6)
	s_barrier
	s_setprio 0
	v_mfma_f32_16x16x32_bf16 v[44:47], v[220:223], v[188:191], v[44:47]
	v_mfma_f32_16x16x32_bf16 v[40:43], v[228:231], v[188:191], v[40:43]
	v_mfma_f32_16x16x32_bf16 v[28:31], v[220:223], v[196:199], v[28:31]
	v_mfma_f32_16x16x32_bf16 v[24:27], v[228:231], v[196:199], v[24:27]
	v_mfma_f32_16x16x32_bf16 v[20:23], v[220:223], v[204:207], v[20:23]
	v_mfma_f32_16x16x32_bf16 v[16:19], v[228:231], v[204:207], v[16:19]
	v_mfma_f32_16x16x32_bf16 v[4:7], v[220:223], v[212:215], v[4:7]
	v_mfma_f32_16x16x32_bf16 v[0:3], v[228:231], v[212:215], v[0:3]
	v_mfma_f32_16x16x32_bf16 v[44:47], v[224:227], v[192:195], v[44:47]
	v_mfma_f32_16x16x32_bf16 v[40:43], v[232:235], v[192:195], v[40:43]
	v_mfma_f32_16x16x32_bf16 v[28:31], v[224:227], v[200:203], v[28:31]
	v_mfma_f32_16x16x32_bf16 v[24:27], v[232:235], v[200:203], v[24:27]
	v_mfma_f32_16x16x32_bf16 v[20:23], v[224:227], v[208:211], v[20:23]
	v_mfma_f32_16x16x32_bf16 v[16:19], v[232:235], v[208:211], v[16:19]
	v_mfma_f32_16x16x32_bf16 v[4:7], v[224:227], v[216:219], v[4:7]
	v_mfma_f32_16x16x32_bf16 v[0:3], v[232:235], v[216:219], v[0:3]
	s_setprio 1
	s_add_i32 s68, 0, 0x18000
	v_add_u32_e32 v144, s68, v135
	s_barrier
	ds_read_b128 v[154:157], v144
	ds_read_b128 v[176:179], v144 offset:1024
	ds_read_b128 v[180:183], v144 offset:2048
	ds_read_b128 v[184:187], v144 offset:3072
	s_add_u32 s28, s28, 0x80000
	s_addc_u32 s29, s29, 0
	s_mov_b32 m0, s44
	v_lshl_add_u64 v[220:221], s[28:29], 0, v[142:143]
	ds_read_b128 v[188:191], v174 offset:32768
	ds_read_b128 v[192:195], v174 offset:33792
	ds_read_b128 v[196:199], v174 offset:34816
	ds_read_b128 v[200:203], v174 offset:35840
	ds_read_b128 v[204:207], v174 offset:36864
	ds_read_b128 v[208:211], v174 offset:37888
	ds_read_b128 v[212:215], v174 offset:38912
	ds_read_b128 v[216:219], v174 offset:39936
	global_load_lds_dwordx4 v[220:221], off
	v_lshl_add_u64 v[220:221], s[28:29], 0, v[138:139]
	s_mov_b32 m0, s45
	s_nop 0
	global_load_lds_dwordx4 v[220:221], off
	s_waitcnt lgkmcnt(8)
	s_barrier
	s_waitcnt lgkmcnt(0)
	s_setprio 0
	s_waitcnt lgkmcnt(0)
	v_mfma_f32_16x16x32_bf16 v[124:127], v[154:157], v[188:191], v[124:127]
	v_mfma_f32_16x16x32_bf16 v[120:123], v[180:183], v[188:191], v[120:123]
	v_mfma_f32_16x16x32_bf16 v[116:119], v[154:157], v[196:199], v[116:119]
	v_mfma_f32_16x16x32_bf16 v[112:115], v[180:183], v[196:199], v[112:115]
	v_mfma_f32_16x16x32_bf16 v[100:103], v[154:157], v[204:207], v[100:103]
	v_mfma_f32_16x16x32_bf16 v[96:99], v[180:183], v[204:207], v[96:99]
	v_mfma_f32_16x16x32_bf16 v[76:79], v[154:157], v[212:215], v[76:79]
	v_mfma_f32_16x16x32_bf16 v[72:75], v[180:183], v[212:215], v[72:75]
	v_mfma_f32_16x16x32_bf16 v[124:127], v[176:179], v[192:195], v[124:127]
	v_mfma_f32_16x16x32_bf16 v[120:123], v[184:187], v[192:195], v[120:123]
	v_mfma_f32_16x16x32_bf16 v[116:119], v[176:179], v[200:203], v[116:119]
	v_mfma_f32_16x16x32_bf16 v[112:115], v[184:187], v[200:203], v[112:115]
	v_mfma_f32_16x16x32_bf16 v[100:103], v[176:179], v[208:211], v[100:103]
	v_mfma_f32_16x16x32_bf16 v[96:99], v[184:187], v[208:211], v[96:99]
	v_mfma_f32_16x16x32_bf16 v[76:79], v[176:179], v[216:219], v[76:79]
	v_mfma_f32_16x16x32_bf16 v[72:75], v[184:187], v[216:219], v[72:75]
	s_setprio 1
	s_barrier
	s_add_i32 s28, 0, 0x1c000
	s_add_i32 s29, s68, s35
	v_add_u32_e32 v144, s28, v135
	v_lshl_add_u64 v[236:237], v[236:237], 0, s[16:17]
	s_mov_b32 m0, s29
	ds_read_b128 v[220:223], v144
	ds_read_b128 v[224:227], v144 offset:1024
	ds_read_b128 v[228:231], v144 offset:2048
	ds_read_b128 v[232:235], v144 offset:3072
	global_load_lds_dwordx4 v[236:237], off
	v_lshl_add_u64 v[236:237], v[238:239], 0, s[16:17]
	s_add_i32 m0, s29, 0x2000
	s_nop 0
	global_load_lds_dwordx4 v[236:237], off
	s_barrier
	s_waitcnt lgkmcnt(0)
	s_setprio 0
	s_waitcnt lgkmcnt(0)
	v_mfma_f32_16x16x32_bf16 v[108:111], v[220:223], v[188:191], v[108:111]
	v_mfma_f32_16x16x32_bf16 v[104:107], v[228:231], v[188:191], v[104:107]
	v_mfma_f32_16x16x32_bf16 v[92:95], v[220:223], v[196:199], v[92:95]
	v_mfma_f32_16x16x32_bf16 v[88:91], v[228:231], v[196:199], v[88:91]
	v_mfma_f32_16x16x32_bf16 v[84:87], v[220:223], v[204:207], v[84:87]
	v_mfma_f32_16x16x32_bf16 v[80:83], v[228:231], v[204:207], v[80:83]
	v_mfma_f32_16x16x32_bf16 v[68:71], v[220:223], v[212:215], v[68:71]
	v_mfma_f32_16x16x32_bf16 v[64:67], v[228:231], v[212:215], v[64:67]
	v_mfma_f32_16x16x32_bf16 v[108:111], v[224:227], v[192:195], v[108:111]
	v_mfma_f32_16x16x32_bf16 v[104:107], v[232:235], v[192:195], v[104:107]
	v_mfma_f32_16x16x32_bf16 v[92:95], v[224:227], v[200:203], v[92:95]
	v_mfma_f32_16x16x32_bf16 v[88:91], v[232:235], v[200:203], v[88:91]
	v_mfma_f32_16x16x32_bf16 v[84:87], v[224:227], v[208:211], v[84:87]
	v_mfma_f32_16x16x32_bf16 v[80:83], v[232:235], v[208:211], v[80:83]
	v_mfma_f32_16x16x32_bf16 v[68:71], v[224:227], v[216:219], v[68:71]
	v_mfma_f32_16x16x32_bf16 v[64:67], v[232:235], v[216:219], v[64:67]
	s_setprio 1
	s_mov_b32 m0, s48
	v_lshl_add_u64 v[236:237], v[240:241], 0, s[16:17]
	s_barrier
	ds_read_b128 v[188:191], v174 offset:49152
	ds_read_b128 v[192:195], v174 offset:50176
	ds_read_b128 v[196:199], v174 offset:51200
	ds_read_b128 v[200:203], v174 offset:52224
	ds_read_b128 v[204:207], v174 offset:53248
	ds_read_b128 v[208:211], v174 offset:54272
	ds_read_b128 v[212:215], v174 offset:55296
	ds_read_b128 v[216:219], v174 offset:56320
	global_load_lds_dwordx4 v[236:237], off
	v_lshl_add_u64 v[236:237], v[242:243], 0, s[16:17]
	s_mov_b32 m0, s49
	s_nop 0
	global_load_lds_dwordx4 v[236:237], off
	s_barrier
; __device__ __forceinline__ unsigned pk_bf16(float lo, float hi) { const f32x2 v = (f32x2){lo, hi}; const bf16v2 b = __builtin_convertvector(v, bf16v2); return __builtin_bit_cast(unsigned, b); }
; #define PG8_STAGE(bufoff, gbase, voff) do { _Pragma("unroll") for (int _i = 0; _i < 2; ++_i) \
;         __builtin_amdgcn_global_load_lds((const unsigned*)((const char*)(gbase) + (voff)[_i]), (LAS unsigned*)(lds + (bufoff) + ldsw + _i * 8192), 16, 0, 0); } while (0)
; #define PG8_BAR __builtin_amdgcn_s_barrier()
; template <class Epi>
; __device__ __forceinline__ void gemm_phase(LAS unsigned char* lds, const Gemm g, const StaticOrder& S, const Epi& E) {
;     ...
;             PG8_BAR; PG8_WAIT_L(0); PG8_MMA(0, 1, At, B1); PG8_BAR;
;             PG8_LDA(At, 1, 1); PG8_STAGE(PG8_SA(1, 0), a3, voffA);
;             PG8_BAR; PG8_WAIT_L(0); PG8_MMA(1, 0, At, B0); PG8_BAR; PG8_SCHED;
;             PG8_STAGE(PG8_SB(1, 1), b3 + hstep, voffB);
;             PG8_WAIT_V(6); PG8_BAR; PG8_MMA(1, 1, At, B1); PG8_BAR;
;     __device__ __forceinline__ void operator()(const f32x4 (&acc)[2][2][4][2], const pg8::Unit& u, int wr, int wc, int fr, int fq) const {
;         const int row0 = u.pm * 256 + wr * 64 + fr, col0 = u.pn * 256 + wc * 32 + 8 * fq;
; #pragma unroll
;         for (int ai = 0; ai < 2; ++ai)
; #pragma unroll
;             for (int m = 0; m < 4; ++m) {
;                 const int row = row0 + ai * 128 + m * 16;
;                 bf16_t* rowp = Z + (size_t)row * LDZ + col0;
;                 const bool last = ((row & 63) == 63) && (row >= MP || (row & (SEQ - 1)) == SEQ - 1);
; #pragma unroll
;                 for (int bj = 0; bj < 2; ++bj) {
;                     const f32x4 v0 = acc[ai][bj][m][0], v1 = acc[ai][bj][m][1];
;                     u32x4 w; w.x = pk_bf16(v0[0], v0[1]); w.y = pk_bf16(v0[2], v0[3]); w.z = pk_bf16(v1[0], v1[1]); w.w = pk_bf16(v1[2], v1[3]);
;                     *(u32x4*)(rowp + bj * 128) = w;
;                     if (last) {
;                         const int c = col0 + bj * 128 - ZC_S;
;                         if (c >= 0 && c < NSHIFT) {
;                             float* o = row < MP ? out + O_SHP + (size_t)(row >> 13) * NSHIFT + c : out + O_SHS + (size_t)((row - MP) >> 6) * NSHIFT + c;
;                             *(f32x4*)o = v0; *(f32x4*)(o + 4) = v1;
;                         }
;                     }
;                 }
	s_waitcnt lgkmcnt(0)
	s_setprio 0
	s_waitcnt lgkmcnt(0)
	v_mfma_f32_16x16x32_bf16 v[60:63], v[154:157], v[188:191], v[60:63]
	v_mfma_f32_16x16x32_bf16 v[56:59], v[180:183], v[188:191], v[56:59]
	v_mfma_f32_16x16x32_bf16 v[52:55], v[154:157], v[196:199], v[52:55]
	v_mfma_f32_16x16x32_bf16 v[48:51], v[180:183], v[196:199], v[48:51]
	v_mfma_f32_16x16x32_bf16 v[36:39], v[154:157], v[204:207], v[36:39]
	v_mfma_f32_16x16x32_bf16 v[32:35], v[180:183], v[204:207], v[32:35]
	v_mfma_f32_16x16x32_bf16 v[12:15], v[154:157], v[212:215], v[12:15]
	v_mfma_f32_16x16x32_bf16 v[8:11], v[180:183], v[212:215], v[8:11]
	v_mfma_f32_16x16x32_bf16 v[60:63], v[176:179], v[192:195], v[60:63]
	v_mfma_f32_16x16x32_bf16 v[56:59], v[184:187], v[192:195], v[56:59]
	v_mfma_f32_16x16x32_bf16 v[52:55], v[176:179], v[200:203], v[52:55]
	v_mfma_f32_16x16x32_bf16 v[48:51], v[184:187], v[200:203], v[48:51]
	v_mfma_f32_16x16x32_bf16 v[36:39], v[176:179], v[208:211], v[36:39]
	v_mfma_f32_16x16x32_bf16 v[32:35], v[184:187], v[208:211], v[32:35]
	v_mfma_f32_16x16x32_bf16 v[12:15], v[176:179], v[216:219], v[12:15]
	v_mfma_f32_16x16x32_bf16 v[8:11], v[184:187], v[216:219], v[8:11]
	s_setprio 1
	s_barrier
	s_add_u32 s26, s26, 0x80080
	s_addc_u32 s27, s27, 0
	s_add_i32 s28, s28, s35
	v_lshl_add_u64 v[154:155], s[26:27], 0, v[140:141]
	s_mov_b32 m0, s28
	s_nop 0
	global_load_lds_dwordx4 v[154:155], off
	v_lshl_add_u64 v[154:155], s[26:27], 0, v[136:137]
	s_add_i32 m0, s28, 0x2000
	s_nop 0
	global_load_lds_dwordx4 v[154:155], off
	s_waitcnt vmcnt(6)
	s_barrier
	s_setprio 0
	v_mfma_f32_16x16x32_bf16 v[44:47], v[220:223], v[188:191], v[44:47]
	v_mfma_f32_16x16x32_bf16 v[40:43], v[228:231], v[188:191], v[40:43]
	v_mfma_f32_16x16x32_bf16 v[28:31], v[220:223], v[196:199], v[28:31]
	v_mfma_f32_16x16x32_bf16 v[24:27], v[228:231], v[196:199], v[24:27]
	v_mfma_f32_16x16x32_bf16 v[20:23], v[220:223], v[204:207], v[20:23]
	v_mfma_f32_16x16x32_bf16 v[16:19], v[228:231], v[204:207], v[16:19]
	v_mfma_f32_16x16x32_bf16 v[4:7], v[220:223], v[212:215], v[4:7]
	v_mfma_f32_16x16x32_bf16 v[0:3], v[228:231], v[212:215], v[0:3]
	v_mfma_f32_16x16x32_bf16 v[44:47], v[224:227], v[192:195], v[44:47]
	v_mfma_f32_16x16x32_bf16 v[40:43], v[232:235], v[192:195], v[40:43]
	v_mfma_f32_16x16x32_bf16 v[28:31], v[224:227], v[200:203], v[28:31]
	v_mfma_f32_16x16x32_bf16 v[24:27], v[232:235], v[200:203], v[24:27]
	v_mfma_f32_16x16x32_bf16 v[20:23], v[224:227], v[208:211], v[20:23]
	v_mfma_f32_16x16x32_bf16 v[16:19], v[232:235], v[208:211], v[16:19]
	v_mfma_f32_16x16x32_bf16 v[4:7], v[224:227], v[216:219], v[4:7]
	v_mfma_f32_16x16x32_bf16 v[0:3], v[232:235], v[216:219], v[0:3]
	s_setprio 1
	s_add_i32 s67, s67, 2
	s_add_u32 s12, s12, 0x100
	s_addc_u32 s13, s13, 0
	s_add_u32 s65, s65, 0x100
	s_addc_u32 s66, s66, 0
	s_cmp_gt_u32 s67, 29
	s_barrier
	s_cbranch_scc0 .LBB0_80
	s_lshl_b32 s7, s31, 8
	s_add_i32 s7, s7, s47
	v_lshl_or_b32 v156, s30, 8, v172
	s_add_i32 s12, s7, 0xffff8000
	v_or_b32_e32 v176, s7, v161
	v_ashrrev_i32_e32 v157, 31, v156
	s_lshr_b32 s63, s12, 6
	s_ashr_i32 s12, s7, 13
	v_mov_b64_e32 v[178:179], s[14:15]
	s_mul_i32 s26, s12, 0xc80
	v_mad_i64_i32 v[180:181], s[12:13], v176, s58, v[178:179]
	v_lshlrev_b64 v[154:155], 1, v[156:157]
	v_cvt_pk_bf16_f32 v108, v108, v109
	v_cvt_pk_bf16_f32 v109, v110, v111
	v_cvt_pk_bf16_f32 v110, v104, v105
	v_or_b32_e32 v104, 16, v176
	v_cvt_pk_bf16_f32 v92, v92, v93
	v_cvt_pk_bf16_f32 v93, v94, v95
	v_cvt_pk_bf16_f32 v94, v88, v89
	v_or_b32_e32 v88, 32, v176
	v_cvt_pk_bf16_f32 v84, v84, v85
	v_cvt_pk_bf16_f32 v85, v86, v87
	v_cvt_pk_bf16_f32 v87, v82, v83
	v_or_b32_e32 v82, 48, v176
	v_lshl_add_u64 v[180:181], v[180:181], 0, v[154:155]
	v_cvt_pk_bf16_f32 v111, v106, v107
	v_mad_i64_i32 v[104:105], s[12:13], v104, s58, v[178:179]
	v_mad_i64_i32 v[88:89], s[12:13], v88, s58, v[178:179]
	v_cvt_pk_bf16_f32 v86, v80, v81
	v_mad_i64_i32 v[80:81], s[12:13], v82, s58, v[178:179]
	v_bitop3_b32 v83, v176, s60, 48 bitop3:0xc8
	global_store_dwordx4 v[180:181], v[108:111], off offset:256
	v_cvt_pk_bf16_f32 v95, v90, v91
	v_cmp_lt_i32_e32 vcc, s59, v82
	v_lshl_add_u64 v[108:109], v[104:105], 0, v[154:155]
	v_cmp_eq_u32_e64 s[12:13], s60, v83
	global_store_dwordx4 v[108:109], v[92:95], off offset:256
	s_or_b64 s[12:13], vcc, s[12:13]
	s_mul_hi_u32 s25, s63, 0x3200
	v_lshl_add_u64 v[92:93], v[88:89], 0, v[154:155]
	s_mulk_i32 s63, 0x3200
	s_ashr_i32 s27, s26, 31
	v_cvt_pk_bf16_f32 v124, v124, v125
	v_cvt_pk_bf16_f32 v125, v126, v127
	v_cvt_pk_bf16_f32 v126, v120, v121
	v_cvt_pk_bf16_f32 v127, v122, v123
	v_cvt_pk_bf16_f32 v104, v116, v117
	v_cvt_pk_bf16_f32 v105, v118, v119
	v_cvt_pk_bf16_f32 v106, v112, v113
	v_cvt_pk_bf16_f32 v107, v114, v115
	v_cvt_pk_bf16_f32 v88, v100, v101
	v_cvt_pk_bf16_f32 v89, v102, v103
	v_cvt_pk_bf16_f32 v90, v96, v97
	v_cvt_pk_bf16_f32 v91, v98, v99
	global_store_dwordx4 v[92:93], v[84:87], off offset:256
	v_lshl_add_u64 v[80:81], v[80:81], 0, v[154:155]
	s_and_b64 s[28:29], s[8:9], s[12:13]
	v_cmp_gt_i32_e32 vcc, s50, v82
	v_cvt_pk_bf16_f32 v82, v76, v77
	v_cvt_pk_bf16_f32 v83, v78, v79
	v_cvt_pk_bf16_f32 v84, v72, v73
	v_cvt_pk_bf16_f32 v85, v74, v75
	v_add_u32_e32 v144, 0xfffff400, v156
	global_store_dwordx4 v[180:181], v[124:127], off
	global_store_dwordx4 v[108:109], v[104:107], off
	global_store_dwordx4 v[92:93], v[88:91], off
	global_store_dwordx4 v[80:81], v[82:85], off
	s_and_saveexec_b64 s[30:31], s[28:29]
	s_cbranch_execz .LBB0_84
	v_cmp_gt_u32_e64 s[12:13], s57, v144
	s_and_b64 exec, exec, s[12:13]
	s_cbranch_execz .LBB0_84
	s_lshl_b64 s[12:13], s[26:27], 2
	s_add_u32 s12, s22, s12
	s_addc_u32 s13, s23, s13
	s_add_u32 s64, s51, s63
	s_addc_u32 s65, s52, s25
	v_mov_b32_e32 v82, s65
	v_mov_b32_e32 v83, s13
	v_cndmask_b32_e32 v83, v82, v83, vcc
	v_mov_b32_e32 v82, s64
	v_mov_b32_e32 v84, s12
	v_cndmask_b32_e32 v82, v82, v84, vcc
	v_lshl_add_u64 v[82:83], v[144:145], 2, v[82:83]
	global_store_dwordx4 v[82:83], v[76:79], off
	global_store_dwordx4 v[82:83], v[72:75], off offset:16

; #define PG8_STAGE(bufoff, gbase, voff) do { _Pragma("unroll") for (int _i = 0; _i < 2; ++_i) \
;         __builtin_amdgcn_global_load_lds((const unsigned*)((const char*)(gbase) + (voff)[_i]), (LAS unsigned*)(lds + (bufoff) + ldsw + _i * 8192), 16, 0, 0); } while (0)
; #define PG8_LDA(dst, b, h) do { _Pragma("unroll") for (int m = 0; m < 4; ++m) _Pragma("unroll") for (int k = 0; k < 2; ++k) dst[m][k] = *(const LAS bf16x8*)(lds + PG8_SA(b, h) + aoff + m * 2048 + k * 1024); } while (0)
; #define PG8_LDB(dst, b, h) do { _Pragma("unroll") for (int n = 0; n < 2; ++n) _Pragma("unroll") for (int k = 0; k < 2; ++k) dst[n][k] = *(const LAS bf16x8*)(lds + PG8_SB(b, h) + boff + n * 2048 + k * 1024); } while (0)
; #define PG8_MMA(ai, bj, At, Bt) do { __builtin_amdgcn_s_setprio(1); _Pragma("unroll") for (int m = 0; m < 4; ++m) _Pragma("unroll") for (int n = 0; n < 2; ++n) _Pragma("unroll") for (int k = 0; k < 2; ++k) \
;         acc[ai][bj][m][n] = __builtin_amdgcn_mfma_f32_16x16x32_bf16(Bt[n][k], At[m][k], acc[ai][bj][m][n], 0, 0, 0); __builtin_amdgcn_s_setprio(0); } while (0)
; #define PG8_WAIT_V(n) asm volatile("s_waitcnt vmcnt(" #n ")" ::: "memory")
; #define PG8_WAIT_L(n) asm volatile("s_waitcnt lgkmcnt(" #n ")" ::: "memory")
; #define PG8_BAR __builtin_amdgcn_s_barrier()
; #define PG8_SCHED __builtin_amdgcn_sched_barrier(0)
; template <class Epi>
; __device__ __forceinline__ void gemm_phase(LAS unsigned char* lds, const Gemm g, const StaticOrder& S, const Epi& E) {
;     ...
;             PG8_LDB(B0, 0, 0); PG8_SCHED; PG8_LDA(At, 0, 0); PG8_STAGE(PG8_SA(1, 1), a1 + hstep, voffA);
;             PG8_WAIT_L(8); PG8_BAR; PG8_WAIT_L(0); PG8_MMA(0, 0, At, B0); PG8_BAR; PG8_SCHED;
;             PG8_LDB(B1, 0, 1); PG8_STAGE(PG8_SB(0, 0), b2, voffB);
;             PG8_BAR; PG8_WAIT_L(0); PG8_MMA(0, 1, At, B1); PG8_BAR;
;             PG8_LDA(At, 0, 1); PG8_STAGE(PG8_SA(0, 0), a2, voffA);
;             PG8_BAR; PG8_WAIT_L(0); PG8_MMA(1, 0, At, B0); PG8_BAR; PG8_SCHED;
;             PG8_STAGE(PG8_SB(0, 1), b2 + hstep, voffB);
;             PG8_WAIT_V(6); PG8_BAR; PG8_MMA(1, 1, At, B1); PG8_BAR;
;             PG8_LDB(B0, 1, 0); PG8_SCHED; PG8_LDA(At, 1, 0); PG8_STAGE(PG8_SA(0, 1), a2 + hstep, voffA);
;             PG8_WAIT_L(8); PG8_BAR; PG8_WAIT_L(0); PG8_MMA(0, 0, At, B0); PG8_BAR; PG8_SCHED;
.LBB0_559:
	ds_read_b128 v[156:159], v133
	ds_read_b128 v[160:163], v133 offset:1024
	ds_read_b128 v[164:167], v133 offset:2048
	ds_read_b128 v[168:171], v133 offset:3072
	s_add_u32 s34, s30, 0xfff80080
	s_addc_u32 s35, s31, -1
	s_cmp_eq_u32 s65, 28
	s_cselect_b32 s41, s25, s35
	s_cselect_b32 s40, s61, s34
	s_cselect_b32 s35, s23, s64
	s_cselect_b32 s34, s62, s63
	v_lshl_add_u64 v[204:205], s[30:31], 0, v[142:143]
	s_add_i32 m0, s21, 0xc000
	ds_read_b128 v[172:175], v153
	ds_read_b128 v[176:179], v153 offset:1024
	ds_read_b128 v[180:183], v153 offset:2048
	ds_read_b128 v[184:187], v153 offset:3072
	ds_read_b128 v[188:191], v153 offset:4096
	ds_read_b128 v[192:195], v153 offset:5120
	ds_read_b128 v[196:199], v153 offset:6144
	ds_read_b128 v[200:203], v153 offset:7168
	global_load_lds_dwordx4 v[204:205], off
	v_lshl_add_u64 v[204:205], s[30:31], 0, v[144:145]
	s_add_i32 m0, s21, 0xe000
	s_nop 0
	global_load_lds_dwordx4 v[204:205], off
	s_waitcnt lgkmcnt(8)
	s_barrier
	s_waitcnt lgkmcnt(0)
	s_setprio 0
	s_waitcnt lgkmcnt(0)
	v_mfma_f32_16x16x32_bf16 v[124:127], v[156:159], v[172:175], v[124:127]
	v_mfma_f32_16x16x32_bf16 v[120:123], v[164:167], v[172:175], v[120:123]
	v_mfma_f32_16x16x32_bf16 v[116:119], v[156:159], v[180:183], v[116:119]
	v_mfma_f32_16x16x32_bf16 v[112:115], v[164:167], v[180:183], v[112:115]
	v_mfma_f32_16x16x32_bf16 v[100:103], v[156:159], v[188:191], v[100:103]
	v_mfma_f32_16x16x32_bf16 v[96:99], v[164:167], v[188:191], v[96:99]
	v_mfma_f32_16x16x32_bf16 v[84:87], v[156:159], v[196:199], v[84:87]
	v_mfma_f32_16x16x32_bf16 v[80:83], v[164:167], v[196:199], v[80:83]
	v_mfma_f32_16x16x32_bf16 v[124:127], v[160:163], v[176:179], v[124:127]
	v_mfma_f32_16x16x32_bf16 v[120:123], v[168:171], v[176:179], v[120:123]
	v_mfma_f32_16x16x32_bf16 v[116:119], v[160:163], v[184:187], v[116:119]
	v_mfma_f32_16x16x32_bf16 v[112:115], v[168:171], v[184:187], v[112:115]
	v_mfma_f32_16x16x32_bf16 v[100:103], v[160:163], v[192:195], v[100:103]
	v_mfma_f32_16x16x32_bf16 v[96:99], v[168:171], v[192:195], v[96:99]
	v_mfma_f32_16x16x32_bf16 v[84:87], v[160:163], v[200:203], v[84:87]
	v_mfma_f32_16x16x32_bf16 v[80:83], v[168:171], v[200:203], v[80:83]
	s_setprio 1
	s_barrier
	s_add_i32 s66, s54, s43
	v_lshl_add_u64 v[220:221], s[34:35], 0, v[138:139]
	s_mov_b32 m0, s66
	ds_read_b128 v[204:207], v154
	ds_read_b128 v[208:211], v154 offset:1024
	ds_read_b128 v[212:215], v154 offset:2048
	ds_read_b128 v[216:219], v154 offset:3072
	global_load_lds_dwordx4 v[220:221], off
	v_lshl_add_u64 v[222:223], s[34:35], 0, v[134:135]
	s_add_i32 m0, s66, 0x2000
	s_nop 0
	global_load_lds_dwordx4 v[222:223], off
	s_barrier
	s_waitcnt lgkmcnt(0)
	s_setprio 0
	s_waitcnt lgkmcnt(0)
	v_mfma_f32_16x16x32_bf16 v[108:111], v[204:207], v[172:175], v[108:111]
	v_mfma_f32_16x16x32_bf16 v[104:107], v[212:215], v[172:175], v[104:107]
	v_mfma_f32_16x16x32_bf16 v[92:95], v[204:207], v[180:183], v[92:95]
	v_mfma_f32_16x16x32_bf16 v[88:91], v[212:215], v[180:183], v[88:91]
	v_mfma_f32_16x16x32_bf16 v[76:79], v[204:207], v[188:191], v[76:79]
	v_mfma_f32_16x16x32_bf16 v[72:75], v[212:215], v[188:191], v[72:75]
	v_mfma_f32_16x16x32_bf16 v[68:71], v[204:207], v[196:199], v[68:71]
	v_mfma_f32_16x16x32_bf16 v[64:67], v[212:215], v[196:199], v[64:67]
	v_mfma_f32_16x16x32_bf16 v[108:111], v[208:211], v[176:179], v[108:111]
	v_mfma_f32_16x16x32_bf16 v[104:107], v[216:219], v[176:179], v[104:107]
	v_mfma_f32_16x16x32_bf16 v[92:95], v[208:211], v[184:187], v[92:95]
	v_mfma_f32_16x16x32_bf16 v[88:91], v[216:219], v[184:187], v[88:91]
	v_mfma_f32_16x16x32_bf16 v[76:79], v[208:211], v[192:195], v[76:79]
	v_mfma_f32_16x16x32_bf16 v[72:75], v[216:219], v[192:195], v[72:75]
	v_mfma_f32_16x16x32_bf16 v[68:71], v[208:211], v[200:203], v[68:71]
	v_mfma_f32_16x16x32_bf16 v[64:67], v[216:219], v[200:203], v[64:67]
	s_setprio 1
	s_mov_b32 m0, s21
	v_lshl_add_u64 v[224:225], s[40:41], 0, v[140:141]
	s_barrier
	ds_read_b128 v[172:175], v153 offset:16384
	ds_read_b128 v[176:179], v153 offset:17408
	ds_read_b128 v[180:183], v153 offset:18432
	ds_read_b128 v[184:187], v153 offset:19456
	ds_read_b128 v[188:191], v153 offset:20480
	ds_read_b128 v[192:195], v153 offset:21504
	ds_read_b128 v[196:199], v153 offset:22528
	ds_read_b128 v[200:203], v153 offset:23552
	global_load_lds_dwordx4 v[224:225], off
	v_lshl_add_u64 v[226:227], s[40:41], 0, v[136:137]
	s_mov_b32 m0, s46
	s_nop 0
	global_load_lds_dwordx4 v[226:227], off
	s_barrier
	s_waitcnt lgkmcnt(0)
	s_setprio 0
	s_waitcnt lgkmcnt(0)
	v_mfma_f32_16x16x32_bf16 v[60:63], v[156:159], v[172:175], v[60:63]
	v_mfma_f32_16x16x32_bf16 v[56:59], v[164:167], v[172:175], v[56:59]
	v_mfma_f32_16x16x32_bf16 v[52:55], v[156:159], v[180:183], v[52:55]
	v_mfma_f32_16x16x32_bf16 v[48:51], v[164:167], v[180:183], v[48:51]
	v_mfma_f32_16x16x32_bf16 v[36:39], v[156:159], v[188:191], v[36:39]
	v_mfma_f32_16x16x32_bf16 v[32:35], v[164:167], v[188:191], v[32:35]
	v_mfma_f32_16x16x32_bf16 v[20:23], v[156:159], v[196:199], v[20:23]
	v_mfma_f32_16x16x32_bf16 v[16:19], v[164:167], v[196:199], v[16:19]
	v_mfma_f32_16x16x32_bf16 v[60:63], v[160:163], v[176:179], v[60:63]
	v_mfma_f32_16x16x32_bf16 v[56:59], v[168:171], v[176:179], v[56:59]
	v_mfma_f32_16x16x32_bf16 v[52:55], v[160:163], v[184:187], v[52:55]
	v_mfma_f32_16x16x32_bf16 v[48:51], v[168:171], v[184:187], v[48:51]
	v_mfma_f32_16x16x32_bf16 v[36:39], v[160:163], v[192:195], v[36:39]
	v_mfma_f32_16x16x32_bf16 v[32:35], v[168:171], v[192:195], v[32:35]
	v_mfma_f32_16x16x32_bf16 v[20:23], v[160:163], v[200:203], v[20:23]
	v_mfma_f32_16x16x32_bf16 v[16:19], v[168:171], v[200:203], v[16:19]
	s_setprio 1
	s_barrier
; #define PG8_STAGE(bufoff, gbase, voff) do { _Pragma("unroll") for (int _i = 0; _i < 2; ++_i) \
;         __builtin_amdgcn_global_load_lds((const unsigned*)((const char*)(gbase) + (voff)[_i]), (LAS unsigned*)(lds + (bufoff) + ldsw + _i * 8192), 16, 0, 0); } while (0)
; #define PG8_LDA(dst, b, h) do { _Pragma("unroll") for (int m = 0; m < 4; ++m) _Pragma("unroll") for (int k = 0; k < 2; ++k) dst[m][k] = *(const LAS bf16x8*)(lds + PG8_SA(b, h) + aoff + m * 2048 + k * 1024); } while (0)
; #define PG8_LDB(dst, b, h) do { _Pragma("unroll") for (int n = 0; n < 2; ++n) _Pragma("unroll") for (int k = 0; k < 2; ++k) dst[n][k] = *(const LAS bf16x8*)(lds + PG8_SB(b, h) + boff + n * 2048 + k * 1024); } while (0)
; #define PG8_MMA(ai, bj, At, Bt) do { __builtin_amdgcn_s_setprio(1); _Pragma("unroll") for (int m = 0; m < 4; ++m) _Pragma("unroll") for (int n = 0; n < 2; ++n) _Pragma("unroll") for (int k = 0; k < 2; ++k) \
;         acc[ai][bj][m][n] = __builtin_amdgcn_mfma_f32_16x16x32_bf16(Bt[n][k], At[m][k], acc[ai][bj][m][n], 0, 0, 0); __builtin_amdgcn_s_setprio(0); } while (0)
; #define PG8_WAIT_V(n) asm volatile("s_waitcnt vmcnt(" #n ")" ::: "memory")
; #define PG8_WAIT_L(n) asm volatile("s_waitcnt lgkmcnt(" #n ")" ::: "memory")
; #define PG8_BAR __builtin_amdgcn_s_barrier()
; #define PG8_SCHED __builtin_amdgcn_sched_barrier(0)
; template <class Epi>
; __device__ __forceinline__ void gemm_phase(LAS unsigned char* lds, const Gemm g, const StaticOrder& S, const Epi& E) {
;     ...
;             PG8_STAGE(PG8_SB(0, 1), b2 + hstep, voffB);
;             PG8_WAIT_V(6); PG8_BAR; PG8_MMA(1, 1, At, B1); PG8_BAR;
;             PG8_LDB(B0, 1, 0); PG8_SCHED; PG8_LDA(At, 1, 0); PG8_STAGE(PG8_SA(0, 1), a2 + hstep, voffA);
;             PG8_WAIT_L(8); PG8_BAR; PG8_WAIT_L(0); PG8_MMA(0, 0, At, B0); PG8_BAR; PG8_SCHED;
;             PG8_LDB(B1, 1, 1); PG8_STAGE(PG8_SB(1, 0), b3, voffB);
;             PG8_BAR; PG8_WAIT_L(0); PG8_MMA(0, 1, At, B1); PG8_BAR;
;             PG8_LDA(At, 1, 1); PG8_STAGE(PG8_SA(1, 0), a3, voffA);
	s_add_u32 s66, s34, 0x80000
	s_addc_u32 s67, s35, 0
	s_add_i32 s68, s55, s43
	v_lshl_add_u64 v[156:157], s[66:67], 0, v[138:139]
	s_mov_b32 m0, s68
	s_nop 0
	global_load_lds_dwordx4 v[156:157], off
	v_lshl_add_u64 v[156:157], s[66:67], 0, v[134:135]
	s_add_i32 m0, s68, 0x2000
	s_nop 0
	global_load_lds_dwordx4 v[156:157], off
	s_waitcnt vmcnt(6)
	s_barrier
	s_setprio 0
	v_mfma_f32_16x16x32_bf16 v[44:47], v[204:207], v[172:175], v[44:47]
	v_mfma_f32_16x16x32_bf16 v[40:43], v[212:215], v[172:175], v[40:43]
	v_mfma_f32_16x16x32_bf16 v[28:31], v[204:207], v[180:183], v[28:31]
	v_mfma_f32_16x16x32_bf16 v[24:27], v[212:215], v[180:183], v[24:27]
	v_mfma_f32_16x16x32_bf16 v[12:15], v[204:207], v[188:191], v[12:15]
	v_mfma_f32_16x16x32_bf16 v[8:11], v[212:215], v[188:191], v[8:11]
	v_mfma_f32_16x16x32_bf16 v[4:7], v[204:207], v[196:199], v[4:7]
	v_mfma_f32_16x16x32_bf16 v[0:3], v[212:215], v[196:199], v[0:3]
	v_mfma_f32_16x16x32_bf16 v[44:47], v[208:211], v[176:179], v[44:47]
	v_mfma_f32_16x16x32_bf16 v[40:43], v[216:219], v[176:179], v[40:43]
	v_mfma_f32_16x16x32_bf16 v[28:31], v[208:211], v[184:187], v[28:31]
	v_mfma_f32_16x16x32_bf16 v[24:27], v[216:219], v[184:187], v[24:27]
	v_mfma_f32_16x16x32_bf16 v[12:15], v[208:211], v[192:195], v[12:15]
	v_mfma_f32_16x16x32_bf16 v[8:11], v[216:219], v[192:195], v[8:11]
	v_mfma_f32_16x16x32_bf16 v[4:7], v[208:211], v[200:203], v[4:7]
	v_mfma_f32_16x16x32_bf16 v[0:3], v[216:219], v[200:203], v[0:3]
	s_setprio 1
	s_add_i32 s66, 0, 0x18000
	v_add_u32_e32 v155, s66, v151
	s_barrier
	ds_read_b128 v[156:159], v155
	ds_read_b128 v[160:163], v155 offset:1024
	ds_read_b128 v[164:167], v155 offset:2048
	ds_read_b128 v[168:171], v155 offset:3072
	s_add_u32 s40, s40, 0x80000
	s_addc_u32 s41, s41, 0
	s_mov_b32 m0, s47
	v_lshl_add_u64 v[204:205], s[40:41], 0, v[140:141]
	ds_read_b128 v[172:175], v153 offset:32768
	ds_read_b128 v[176:179], v153 offset:33792
	ds_read_b128 v[180:183], v153 offset:34816
	ds_read_b128 v[184:187], v153 offset:35840
	ds_read_b128 v[188:191], v153 offset:36864
	ds_read_b128 v[192:195], v153 offset:37888
	ds_read_b128 v[196:199], v153 offset:38912
	ds_read_b128 v[200:203], v153 offset:39936
	global_load_lds_dwordx4 v[204:205], off
	v_lshl_add_u64 v[204:205], s[40:41], 0, v[136:137]
	s_mov_b32 m0, s48
	s_nop 0
	global_load_lds_dwordx4 v[204:205], off
	s_waitcnt lgkmcnt(8)
	s_barrier
	s_waitcnt lgkmcnt(0)
	s_setprio 0
	s_waitcnt lgkmcnt(0)
	v_mfma_f32_16x16x32_bf16 v[124:127], v[156:159], v[172:175], v[124:127]
	v_mfma_f32_16x16x32_bf16 v[120:123], v[164:167], v[172:175], v[120:123]
	v_mfma_f32_16x16x32_bf16 v[116:119], v[156:159], v[180:183], v[116:119]
	v_mfma_f32_16x16x32_bf16 v[112:115], v[164:167], v[180:183], v[112:115]
	v_mfma_f32_16x16x32_bf16 v[100:103], v[156:159], v[188:191], v[100:103]
	v_mfma_f32_16x16x32_bf16 v[96:99], v[164:167], v[188:191], v[96:99]
	v_mfma_f32_16x16x32_bf16 v[84:87], v[156:159], v[196:199], v[84:87]
	v_mfma_f32_16x16x32_bf16 v[80:83], v[164:167], v[196:199], v[80:83]
	v_mfma_f32_16x16x32_bf16 v[124:127], v[160:163], v[176:179], v[124:127]
	v_mfma_f32_16x16x32_bf16 v[120:123], v[168:171], v[176:179], v[120:123]
	v_mfma_f32_16x16x32_bf16 v[116:119], v[160:163], v[184:187], v[116:119]
	v_mfma_f32_16x16x32_bf16 v[112:115], v[168:171], v[184:187], v[112:115]
	v_mfma_f32_16x16x32_bf16 v[100:103], v[160:163], v[192:195], v[100:103]
	v_mfma_f32_16x16x32_bf16 v[96:99], v[168:171], v[192:195], v[96:99]
	v_mfma_f32_16x16x32_bf16 v[84:87], v[160:163], v[200:203], v[84:87]
	v_mfma_f32_16x16x32_bf16 v[80:83], v[168:171], v[200:203], v[80:83]
	s_setprio 1
	s_barrier
	s_add_i32 s40, 0, 0x1c000
	s_add_i32 s41, s66, s43
	v_add_u32_e32 v155, s40, v151
	v_lshl_add_u64 v[220:221], v[220:221], 0, s[12:13]
	s_mov_b32 m0, s41
	ds_read_b128 v[204:207], v155
	ds_read_b128 v[208:211], v155 offset:1024
	ds_read_b128 v[212:215], v155 offset:2048
	ds_read_b128 v[216:219], v155 offset:3072
	global_load_lds_dwordx4 v[220:221], off
	v_lshl_add_u64 v[220:221], v[222:223], 0, s[12:13]
	s_add_i32 m0, s41, 0x2000
	s_nop 0
	global_load_lds_dwordx4 v[220:221], off
	s_barrier
	s_waitcnt lgkmcnt(0)
	s_setprio 0
	s_waitcnt lgkmcnt(0)
	v_mfma_f32_16x16x32_bf16 v[108:111], v[204:207], v[172:175], v[108:111]
	v_mfma_f32_16x16x32_bf16 v[104:107], v[212:215], v[172:175], v[104:107]
	v_mfma_f32_16x16x32_bf16 v[92:95], v[204:207], v[180:183], v[92:95]
	v_mfma_f32_16x16x32_bf16 v[88:91], v[212:215], v[180:183], v[88:91]
	v_mfma_f32_16x16x32_bf16 v[76:79], v[204:207], v[188:191], v[76:79]
	v_mfma_f32_16x16x32_bf16 v[72:75], v[212:215], v[188:191], v[72:75]
	v_mfma_f32_16x16x32_bf16 v[68:71], v[204:207], v[196:199], v[68:71]
	v_mfma_f32_16x16x32_bf16 v[64:67], v[212:215], v[196:199], v[64:67]
	v_mfma_f32_16x16x32_bf16 v[108:111], v[208:211], v[176:179], v[108:111]
	v_mfma_f32_16x16x32_bf16 v[104:107], v[216:219], v[176:179], v[104:107]
	v_mfma_f32_16x16x32_bf16 v[92:95], v[208:211], v[184:187], v[92:95]
	v_mfma_f32_16x16x32_bf16 v[88:91], v[216:219], v[184:187], v[88:91]
	v_mfma_f32_16x16x32_bf16 v[76:79], v[208:211], v[192:195], v[76:79]
	v_mfma_f32_16x16x32_bf16 v[72:75], v[216:219], v[192:195], v[72:75]
	v_mfma_f32_16x16x32_bf16 v[68:71], v[208:211], v[200:203], v[68:71]
	v_mfma_f32_16x16x32_bf16 v[64:67], v[216:219], v[200:203], v[64:67]
	s_setprio 1
	s_mov_b32 m0, s50
	v_lshl_add_u64 v[220:221], v[224:225], 0, s[12:13]
	s_barrier
	ds_read_b128 v[172:175], v153 offset:49152
	ds_read_b128 v[176:179], v153 offset:50176
	ds_read_b128 v[180:183], v153 offset:51200
	ds_read_b128 v[184:187], v153 offset:52224
	ds_read_b128 v[188:191], v153 offset:53248
	ds_read_b128 v[192:195], v153 offset:54272
	ds_read_b128 v[196:199], v153 offset:55296
	ds_read_b128 v[200:203], v153 offset:56320
	global_load_lds_dwordx4 v[220:221], off
	v_lshl_add_u64 v[220:221], v[226:227], 0, s[12:13]
	s_mov_b32 m0, s51
	s_nop 0
	global_load_lds_dwordx4 v[220:221], off
	s_barrier
; #define PG8_STAGE(bufoff, gbase, voff) do { _Pragma("unroll") for (int _i = 0; _i < 2; ++_i) \
;         __builtin_amdgcn_global_load_lds((const unsigned*)((const char*)(gbase) + (voff)[_i]), (LAS unsigned*)(lds + (bufoff) + ldsw + _i * 8192), 16, 0, 0); } while (0)
; #define PG8_LDA(dst, b, h) do { _Pragma("unroll") for (int m = 0; m < 4; ++m) _Pragma("unroll") for (int k = 0; k < 2; ++k) dst[m][k] = *(const LAS bf16x8*)(lds + PG8_SA(b, h) + aoff + m * 2048 + k * 1024); } while (0)
; #define PG8_MMA(ai, bj, At, Bt) do { __builtin_amdgcn_s_setprio(1); _Pragma("unroll") for (int m = 0; m < 4; ++m) _Pragma("unroll") for (int n = 0; n < 2; ++n) _Pragma("unroll") for (int k = 0; k < 2; ++k) \
;         acc[ai][bj][m][n] = __builtin_amdgcn_mfma_f32_16x16x32_bf16(Bt[n][k], At[m][k], acc[ai][bj][m][n], 0, 0, 0); __builtin_amdgcn_s_setprio(0); } while (0)
; #define PG8_WAIT_V(n) asm volatile("s_waitcnt vmcnt(" #n ")" ::: "memory")
; #define PG8_WAIT_L(n) asm volatile("s_waitcnt lgkmcnt(" #n ")" ::: "memory")
; #define PG8_BAR __builtin_amdgcn_s_barrier()
; #define PG8_SCHED __builtin_amdgcn_sched_barrier(0)
; template <class Epi>
; __device__ __forceinline__ void gemm_phase(LAS unsigned char* lds, const Gemm g, const StaticOrder& S, const Epi& E) {
;     ...
;             PG8_BAR; PG8_WAIT_L(0); PG8_MMA(0, 1, At, B1); PG8_BAR;
;             PG8_LDA(At, 1, 1); PG8_STAGE(PG8_SA(1, 0), a3, voffA);
;             PG8_BAR; PG8_WAIT_L(0); PG8_MMA(1, 0, At, B0); PG8_BAR; PG8_SCHED;
;             PG8_STAGE(PG8_SB(1, 1), b3 + hstep, voffB);
;             PG8_WAIT_V(6); PG8_BAR; PG8_MMA(1, 1, At, B1); PG8_BAR;
	s_waitcnt lgkmcnt(0)
	s_setprio 0
	s_waitcnt lgkmcnt(0)
	v_mfma_f32_16x16x32_bf16 v[60:63], v[156:159], v[172:175], v[60:63]
	v_mfma_f32_16x16x32_bf16 v[56:59], v[164:167], v[172:175], v[56:59]
	v_mfma_f32_16x16x32_bf16 v[52:55], v[156:159], v[180:183], v[52:55]
	v_mfma_f32_16x16x32_bf16 v[48:51], v[164:167], v[180:183], v[48:51]
	v_mfma_f32_16x16x32_bf16 v[36:39], v[156:159], v[188:191], v[36:39]
	v_mfma_f32_16x16x32_bf16 v[32:35], v[164:167], v[188:191], v[32:35]
	v_mfma_f32_16x16x32_bf16 v[20:23], v[156:159], v[196:199], v[20:23]
	v_mfma_f32_16x16x32_bf16 v[16:19], v[164:167], v[196:199], v[16:19]
	v_mfma_f32_16x16x32_bf16 v[60:63], v[160:163], v[176:179], v[60:63]
	v_mfma_f32_16x16x32_bf16 v[56:59], v[168:171], v[176:179], v[56:59]
	v_mfma_f32_16x16x32_bf16 v[52:55], v[160:163], v[184:187], v[52:55]
	v_mfma_f32_16x16x32_bf16 v[48:51], v[168:171], v[184:187], v[48:51]
	v_mfma_f32_16x16x32_bf16 v[36:39], v[160:163], v[192:195], v[36:39]
	v_mfma_f32_16x16x32_bf16 v[32:35], v[168:171], v[192:195], v[32:35]
	v_mfma_f32_16x16x32_bf16 v[20:23], v[160:163], v[200:203], v[20:23]
	v_mfma_f32_16x16x32_bf16 v[16:19], v[168:171], v[200:203], v[16:19]
	s_setprio 1
	s_barrier
	s_add_u32 s34, s34, 0x80080
	s_addc_u32 s35, s35, 0
	s_add_i32 s40, s40, s43
	v_lshl_add_u64 v[156:157], s[34:35], 0, v[138:139]
	s_mov_b32 m0, s40
	s_nop 0
	global_load_lds_dwordx4 v[156:157], off
	v_lshl_add_u64 v[156:157], s[34:35], 0, v[134:135]
	s_add_i32 m0, s40, 0x2000
	s_nop 0
	global_load_lds_dwordx4 v[156:157], off
	s_waitcnt vmcnt(6)
	s_barrier
	s_setprio 0
	v_mfma_f32_16x16x32_bf16 v[44:47], v[204:207], v[172:175], v[44:47]
	v_mfma_f32_16x16x32_bf16 v[40:43], v[212:215], v[172:175], v[40:43]
	v_mfma_f32_16x16x32_bf16 v[28:31], v[204:207], v[180:183], v[28:31]
	v_mfma_f32_16x16x32_bf16 v[24:27], v[212:215], v[180:183], v[24:27]
	v_mfma_f32_16x16x32_bf16 v[12:15], v[204:207], v[188:191], v[12:15]
	v_mfma_f32_16x16x32_bf16 v[8:11], v[212:215], v[188:191], v[8:11]
	v_mfma_f32_16x16x32_bf16 v[4:7], v[204:207], v[196:199], v[4:7]
	v_mfma_f32_16x16x32_bf16 v[0:3], v[212:215], v[196:199], v[0:3]
	v_mfma_f32_16x16x32_bf16 v[44:47], v[208:211], v[176:179], v[44:47]
	v_mfma_f32_16x16x32_bf16 v[40:43], v[216:219], v[176:179], v[40:43]
	v_mfma_f32_16x16x32_bf16 v[28:31], v[208:211], v[184:187], v[28:31]
	v_mfma_f32_16x16x32_bf16 v[24:27], v[216:219], v[184:187], v[24:27]
	v_mfma_f32_16x16x32_bf16 v[12:15], v[208:211], v[192:195], v[12:15]
	v_mfma_f32_16x16x32_bf16 v[8:11], v[216:219], v[192:195], v[8:11]
	v_mfma_f32_16x16x32_bf16 v[4:7], v[208:211], v[200:203], v[4:7]
	v_mfma_f32_16x16x32_bf16 v[0:3], v[216:219], v[200:203], v[0:3]
	s_setprio 1
	s_add_i32 s65, s65, 2
	s_add_u32 s30, s30, 0x100
	s_addc_u32 s31, s31, 0
	s_add_u32 s63, s63, 0x100
	s_addc_u32 s64, s64, 0
	s_cmp_gt_u32 s65, 29
	s_barrier
	s_cbranch_scc0 .LBB0_559
; __device__ __forceinline__ unsigned pk_bf16(float lo, float hi) { const f32x2 v = (f32x2){lo, hi}; const bf16v2 b = __builtin_convertvector(v, bf16v2); return __builtin_bit_cast(unsigned, b); }
; #define PG8_WAIT_V(n) asm volatile("s_waitcnt vmcnt(" #n ")" ::: "memory")
; #define PG8_BAR __builtin_amdgcn_s_barrier()
; template <class Epi>
; __device__ __forceinline__ void gemm_phase(LAS unsigned char* lds, const Gemm g, const StaticOrder& S, const Epi& E) {
;     ...
;         if (!has_next) break;
; #pragma unroll
;         for (int a = 0; a < 2; ++a)
; #pragma unroll
;             for (int b = 0; b < 2; ++b)
; #pragma unroll
;                 for (int m = 0; m < 4; ++m)
; #pragma unroll
;                     for (int n = 0; n < 2; ++n) acc[a][b][m][n] = (f32x4){0.f, 0.f, 0.f, 0.f};
;         cur = nxt; cA = nA; cB = nB; ++ui;
;     }
;     PG8_WAIT_V(0);
;     if (wr == 0) PG8_BAR;
;     __device__ __forceinline__ void operator()(const f32x4 (&acc)[2][2][4][2], const pg8::Unit& u, int wr, int wc, int fr, int fq) const {
;         const int row0 = u.pm * 256 + wr * 64 + fr, col0 = u.pn * 256 + wc * 32 + 8 * fq;
; #pragma unroll
;         for (int ai = 0; ai < 2; ++ai)
; #pragma unroll
;             for (int m = 0; m < 4; ++m) {
;                 const int row = row0 + ai * 128 + m * 16;
;                 bf16_t* orow = yb + (size_t)row * DM + col0;
; #pragma unroll
;                 for (int bj = 0; bj < 2; ++bj) {
;                     const f32x4 v0 = acc[ai][bj][m][0], v1 = acc[ai][bj][m][1];
;                     *(u32x4*)(orow + bj * 128) = (u32x4){pk_bf16(v0[0], v0[1]), pk_bf16(v0[2], v0[3]), pk_bf16(v1[0], v1[1]), pk_bf16(v1[2], v1[3])};
;                 }
;             }
	v_lshl_add_u32 v156, s20, 8, v150
	v_lshl_or_b32 v158, s60, 8, v152
	v_ashrrev_i32_e32 v157, 31, v156
	v_ashrrev_i32_e32 v159, 31, v158
	v_lshlrev_b64 v[160:161], 12, v[156:157]
	v_lshl_add_u64 v[160:161], s[6:7], 0, v[160:161]
	v_lshlrev_b64 v[158:159], 1, v[158:159]
	v_lshl_add_u64 v[160:161], v[160:161], 0, v[158:159]
	v_cvt_pk_bf16_f32 v60, v60, v61
	v_cvt_pk_bf16_f32 v61, v62, v63
	v_cvt_pk_bf16_f32 v62, v56, v57
	v_add_co_u32_e32 v56, vcc, s56, v160
	v_cvt_pk_bf16_f32 v68, v68, v69
	v_cvt_pk_bf16_f32 v69, v70, v71
	v_cvt_pk_bf16_f32 v70, v64, v65
	v_lshl_add_u64 v[64:65], v[160:161], 0, s[10:11]
	v_addc_co_u32_e32 v57, vcc, 0, v161, vcc
	v_cvt_pk_bf16_f32 v44, v44, v45
	v_cvt_pk_bf16_f32 v45, v46, v47
	v_cvt_pk_bf16_f32 v46, v40, v41
	v_cvt_pk_bf16_f32 v47, v42, v43
	v_cvt_pk_bf16_f32 v108, v108, v109
	v_cvt_pk_bf16_f32 v109, v110, v111
	v_cvt_pk_bf16_f32 v110, v104, v105
	v_or_b32_e32 v104, 16, v156
	global_store_dwordx4 v[64:65], v[44:47], off offset:256
	v_ashrrev_i32_e32 v105, 31, v104
	v_cvt_pk_bf16_f32 v92, v92, v93
	v_add_co_u32_e32 v46, vcc, s57, v160
	v_cvt_pk_bf16_f32 v93, v94, v95
	v_cvt_pk_bf16_f32 v94, v88, v89
	v_or_b32_e32 v88, 32, v156
	v_lshl_add_u64 v[44:45], v[160:161], 0, s[14:15]
	v_addc_co_u32_e32 v47, vcc, 0, v161, vcc
	v_cvt_pk_bf16_f32 v28, v28, v29
	v_cvt_pk_bf16_f32 v29, v30, v31
	v_cvt_pk_bf16_f32 v30, v24, v25
	v_cvt_pk_bf16_f32 v31, v26, v27
	v_lshlrev_b64 v[104:105], 12, v[104:105]
	v_ashrrev_i32_e32 v89, 31, v88
	v_cvt_pk_bf16_f32 v76, v76, v77
	v_cvt_pk_bf16_f32 v77, v78, v79
	v_cvt_pk_bf16_f32 v78, v72, v73
	v_or_b32_e32 v72, 48, v156
	global_store_dwordx4 v[44:45], v[28:31], off offset:256
	v_cvt_pk_bf16_f32 v111, v106, v107
	v_lshl_add_u64 v[104:105], s[6:7], 0, v[104:105]
	v_add_co_u32_e32 v30, vcc, s58, v160
	v_lshlrev_b64 v[88:89], 12, v[88:89]
	v_ashrrev_i32_e32 v73, 31, v72
	v_lshl_add_u64 v[28:29], v[160:161], 0, s[16:17]
	v_addc_co_u32_e32 v31, vcc, 0, v161, vcc
	v_cvt_pk_bf16_f32 v12, v12, v13
	v_cvt_pk_bf16_f32 v13, v14, v15
	v_cvt_pk_bf16_f32 v14, v8, v9
	v_cvt_pk_bf16_f32 v15, v10, v11
	global_store_dwordx4 v[160:161], v[108:111], off offset:256
	v_cvt_pk_bf16_f32 v95, v90, v91
	v_lshl_add_u64 v[88:89], s[6:7], 0, v[88:89]
	v_lshl_add_u64 v[108:109], v[104:105], 0, v[158:159]
	v_lshlrev_b64 v[72:73], 12, v[72:73]
	global_store_dwordx4 v[28:29], v[12:15], off offset:256
	global_store_dwordx4 v[108:109], v[92:95], off offset:256
	v_cvt_pk_bf16_f32 v79, v74, v75
	v_add_co_u32_e32 v14, vcc, s59, v160
	v_lshl_add_u64 v[92:93], v[88:89], 0, v[158:159]
	v_lshl_add_u64 v[72:73], s[6:7], 0, v[72:73]
	v_addc_co_u32_e32 v15, vcc, 0, v161, vcc
	v_cvt_pk_bf16_f32 v124, v124, v125
	v_cvt_pk_bf16_f32 v125, v126, v127
	v_cvt_pk_bf16_f32 v126, v120, v121
	v_cvt_pk_bf16_f32 v127, v122, v123
	v_cvt_pk_bf16_f32 v104, v116, v117
	v_cvt_pk_bf16_f32 v105, v118, v119
	v_cvt_pk_bf16_f32 v106, v112, v113
	v_cvt_pk_bf16_f32 v107, v114, v115
	v_cvt_pk_bf16_f32 v88, v100, v101
	v_cvt_pk_bf16_f32 v89, v102, v103
	v_cvt_pk_bf16_f32 v90, v96, v97
	v_cvt_pk_bf16_f32 v91, v98, v99
	global_store_dwordx4 v[92:93], v[76:79], off offset:256
	v_cvt_pk_bf16_f32 v74, v80, v81
	v_cvt_pk_bf16_f32 v75, v82, v83
	v_lshl_add_u64 v[76:77], v[72:73], 0, v[158:159]
	v_cvt_pk_bf16_f32 v72, v84, v85
	v_cvt_pk_bf16_f32 v73, v86, v87
	v_cvt_pk_bf16_f32 v71, v66, v67
	v_cvt_pk_bf16_f32 v63, v58, v59
	v_cvt_pk_bf16_f32 v40, v52, v53
	v_cvt_pk_bf16_f32 v41, v54, v55
	v_cvt_pk_bf16_f32 v42, v48, v49
	v_cvt_pk_bf16_f32 v43, v50, v51
	v_cvt_pk_bf16_f32 v24, v36, v37
	v_cvt_pk_bf16_f32 v25, v38, v39
	v_cvt_pk_bf16_f32 v26, v32, v33
	v_cvt_pk_bf16_f32 v27, v34, v35
	v_lshl_add_u64 v[12:13], v[160:161], 0, s[18:19]
	v_cvt_pk_bf16_f32 v8, v20, v21
	v_cvt_pk_bf16_f32 v9, v22, v23
	v_cvt_pk_bf16_f32 v10, v16, v17
	v_cvt_pk_bf16_f32 v11, v18, v19
	v_cvt_pk_bf16_f32 v4, v4, v5
	v_cvt_pk_bf16_f32 v5, v6, v7
	v_cvt_pk_bf16_f32 v6, v0, v1
	v_cvt_pk_bf16_f32 v7, v2, v3
	s_and_b64 vcc, exec, s[8:9]
	s_mov_b32 s60, s22
	s_mov_b32 s20, s24
	s_mov_b64 s[34:35], s[28:29]
	s_mov_b64 s[30:31], s[26:27]
	s_mov_b32 s40, s70
	global_store_dwordx4 v[160:161], v[124:127], off
	global_store_dwordx4 v[108:109], v[104:107], off
	global_store_dwordx4 v[92:93], v[88:91], off
	global_store_dwordx4 v[76:77], v[72:75], off
	global_store_dwordx4 v[76:77], v[68:71], off offset:256
	global_store_dwordx4 v[56:57], v[60:63], off
	global_store_dwordx4 v[46:47], v[40:43], off
	global_store_dwordx4 v[30:31], v[24:27], off
	global_store_dwordx4 v[14:15], v[8:11], off
	global_store_dwordx4 v[12:13], v[4:7], off offset:256
	s_cbranch_vccnz .Lg2_exit
	s_cmp_lg_u32 s49, 4
	s_cbranch_scc1 .LBB0_556
	s_waitcnt vmcnt(0)
	s_barrier
	s_lshr_b32 s8, s42, 6
	s_cmp_lg_u32 s8, 4
	s_cbranch_scc1 .LBB0_556
	buffer_wbl2 sc1
	s_waitcnt vmcnt(0)
	s_mov_b64 s[8:9], exec
	s_mov_b64 exec, 1
	v_mov_b32_e32 v0, 0
	v_mov_b32_e32 v1, 1
	global_atomic_add v0, v1, s[36:37] offset:256
	s_mov_b64 exec, s[8:9]
	s_branch .LBB0_556
